# weight conversion items software-pipelined: next tile loads issued before the LDS read-back and stores of the current item, all norm_gain scale loads in flight together
# baseline (speedup 1.0000x reference)
; #define LAS __attribute__((address_space(3)))
; __device__ __forceinline__ int launder(int v) { asm volatile("" : "+v"(v)); return v; }
; __device__ __forceinline__ void conv_item(const Params& p, int l, int t, LAS unsigned char* lds, int tid) {
;     LAS float* tile = (LAS float*)lds;
;     if (t < 2048) { const int kt = t >> 6, nt_ = t & 63;
;         tr_tile(tile, p.w_in + (size_t)l * D * NIN, NIN, (bf16_t*)(pws(p) + OFF_WIN + l * SZ_WIN), D, kt * 64, nt_ * 256, p.norm_gain + l * D, nullptr, tid);
;     } else if (t < 2112) { const int g = (t - 2048) >> 4, tt = (t - 2048) & 15, kt = tt >> 1, nt_ = tt & 1;
;         tr_tile(tile, p.pool_w + ((size_t)l * 4 + g) * 512 * 512, 512, (bf16_t*)(pws(p) + OFF_WPOOL + l * SZ_WPOOL) + (size_t)g * 512 * 512, 512, kt * 64, nt_ * 256, nullptr, p.pool_scale + (size_t)l * D + g * 512, tid);
;     } else { const int j = (t - 2112) >> 8, tt = (t - 2112) & 255, kt = tt >> 3, nt_ = tt & 7;
;         const float* src = (j == 0 ? p.proj_pool : j == 1 ? p.proj_ret : p.w_out) + (size_t)l * D * D;
;         bf16_t* dst = j == 2 ? (bf16_t*)(pws(p) + OFF_WOUT + l * SZ_WOUT) : (bf16_t*)(pws(p) + OFF_WPR + l * SZ_WPR) + (size_t)j * D * D;
;         tr_tile(tile, src, D, dst, D, kt * 64, nt_ * 256, nullptr, nullptr, tid);
;     }
; }
; __device__ __forceinline__ void run_phase(const Params& p, int ph, LAS unsigned char* lds, const int tid, const int bid) {
;     ...
;         if (l == 0 && bid >= 40) for (int it = 1440 + bid - 40; it < 2880; it += G - 40) conv_item(p, 1, it, lds, launder(tid)); }
.LBB0_96:
	s_cmp_gt_i32 s82, 39
	s_cselect_b64 s[6:7], -1, 0
	s_and_b64 s[0:1], s[0:1], s[6:7]
	s_cmpk_lt_u32 s82, 0x5c8
	s_cselect_b64 s[6:7], -1, 0
	s_and_b64 s[0:1], s[0:1], s[6:7]
	s_andn2_b64 vcc, exec, s[0:1]
	s_cbranch_vccnz .LBB0_139
	s_add_i32 s18, s82, 0x578
	s_add_i32 s19, s42, 0xffffffd8
	s_movk_i32 s20, 0xb40
	s_mov_b32 s21, 1
	s_mov_b32 s22, 2
	s_branch .Lcva_run
.Lcva_run:
	v_readlane_b32 s6, v253, 1
	v_readlane_b32 s7, v253, 2
	v_readlane_b32 s16, v254, 20
	v_readlane_b32 s17, v254, 21
	s_add_u32 s6, s6, 0xffffff78
	s_addc_u32 s7, s7, -1
	s_load_dwordx2 s[8:9], s[6:7], 0x40
	s_load_dwordx4 s[12:15], s[6:7], 0x50
	s_load_dwordx2 s[10:11], s[6:7], 0x60
	v_lshrrev_b32_e32 v2, 6, v244
	v_and_b32_e32 v3, 63, v244
	v_lshrrev_b32_e32 v4, 4, v244
	v_and_b32_e32 v5, 15, v244
	v_lshlrev_b32_e32 v6, 2, v2
	s_movk_i32 s38, 0x404
	v_mul_u32_u24_e32 v8, s38, v2
	v_lshlrev_b32_e32 v3, 4, v3
	s_movk_i32 s38, 0x1010
	v_mul_u32_u24_e32 v7, s38, v5
	v_lshlrev_b32_e32 v5, 3, v5
	v_add_u32_e32 v8, v8, v3
	v_lshl_add_u32 v7, v4, 2, v7
	v_add_u32_e32 v9, 0x2020, v8
	v_add_u32_e32 v10, 0x4040, v8
	v_add_u32_e32 v11, 0x6060, v8
	v_add_u32_e32 v12, 0x8080, v8
	v_add_u32_e32 v13, 0xa0a0, v8
	v_add_u32_e32 v14, 0xc0c0, v8
	v_add_u32_e32 v15, 0xe0e0, v8
	s_waitcnt lgkmcnt(0)
	s_mov_b32 s23, s18
	s_cmpk_lt_u32 s23, 0x800
	s_cbranch_scc0 .Lcva_dp_k12
	s_lshr_b32 s38, s23, 6
	s_and_b32 s39, s23, 63
	s_lshl_b32 s6, s21, 27
	s_lshl_b32 s7, s38, 22
	s_add_u32 s6, s6, s7
	s_lshl_b32 s7, s39, 10
	s_add_u32 s6, s6, s7
	s_add_u32 s24, s56, s6
	s_addc_u32 s25, s57, 0
	s_lshl_b32 s6, s21, 26
	s_lshl_b32 s7, s39, 20
	s_add_u32 s6, s6, s7
	s_lshl_b32 s7, s38, 7
	s_add_u32 s6, s6, s7
	s_add_u32 s26, s16, s6
	s_addc_u32 s27, s17, 0
	s_lshl_b32 s6, s21, 13
	s_lshl_b32 s7, s38, 8
	s_add_u32 s6, s6, s7
	s_add_u32 s32, s54, s6
	s_addc_u32 s33, s55, 0
	s_mov_b32 s36, 16
	s_mov_b32 s37, 12
	s_mov_b32 s34, 0
	s_branch .Lcva_dp_done
.Lcva_dp_k12:
	s_cmpk_lt_u32 s23, 0x840
	s_cbranch_scc0 .Lcva_dp_k2
	s_sub_u32 s6, s23, 0x800
	s_lshr_b32 s7, s6, 4
	s_bfe_u32 s38, s6, 0x30001
	s_and_b32 s39, s6, 1
	s_lshl_b32 s6, s21, 22
	s_lshl_b32 s24, s7, 20
	s_add_u32 s6, s6, s24
	s_lshl_b32 s24, s38, 17
	s_add_u32 s6, s6, s24
	s_lshl_b32 s24, s39, 10
	s_add_u32 s6, s6, s24
	s_add_u32 s24, s58, s6
	s_addc_u32 s25, s59, 0
	s_lshl_b32 s6, s21, 21
	s_add_u32 s6, s6, 0x8000000
	s_lshl_b32 s26, s7, 19
	s_add_u32 s6, s6, s26
	s_lshl_b32 s26, s39, 18
	s_add_u32 s6, s6, s26
	s_lshl_b32 s26, s38, 7
	s_add_u32 s6, s6, s26
	s_add_u32 s26, s16, s6
	s_addc_u32 s27, s17, 0
	s_lshl_b32 s6, s21, 13
	s_lshl_b32 s7, s7, 11
	s_add_u32 s6, s6, s7
	s_lshl_b32 s7, s39, 10
	s_add_u32 s6, s6, s7
	s_add_u32 s32, s8, s6
	s_addc_u32 s33, s9, 0
	s_mov_b32 s36, 11
	s_mov_b32 s37, 10
	s_mov_b32 s34, 1
	s_branch .Lcva_dp_done
.Lcva_dp_k2:
	s_sub_u32 s6, s23, 0x840
	s_lshr_b32 s7, s6, 8
	s_bfe_u32 s38, s6, 0x50003
	s_and_b32 s39, s6, 7
	s_cmp_eq_u32 s7, 0
	s_cselect_b32 s24, s12, s14
	s_cselect_b32 s25, s13, s15
	s_cmp_eq_u32 s7, 2
	s_cselect_b32 s24, s10, s24
	s_cselect_b32 s25, s11, s25
	s_lshl_b32 s6, s21, 24
	s_lshl_b32 s26, s38, 19
	s_add_u32 s6, s6, s26
	s_lshl_b32 s26, s39, 10
	s_add_u32 s6, s6, s26
	s_add_u32 s24, s24, s6
	s_addc_u32 s25, s25, 0
	s_lshl_b32 s6, s21, 24
	s_lshl_b32 s26, s7, 23
	s_add_u32 s6, s6, s26
	s_add_u32 s6, s6, 0x8400000
	s_lshl_b32 s26, s21, 23
	s_add_u32 s26, s26, 0xa400000
	s_cmp_eq_u32 s7, 2
	s_cselect_b32 s6, s26, s6
	s_lshl_b32 s26, s39, 20
	s_add_u32 s6, s6, s26
	s_lshl_b32 s26, s38, 7
	s_add_u32 s6, s6, s26
	s_add_u32 s26, s16, s6
	s_addc_u32 s27, s17, 0
	s_mov_b32 s36, 13
	s_mov_b32 s37, 12
	s_mov_b32 s34, 2
; #define LAS __attribute__((address_space(3)))
; __device__ __forceinline__ void tr_tile(LAS float* tile, const float* src, int N, bf16_t* dst, int Kd, int k0, int n0, const float* scale, const float* nscale, int tid) {
;     constexpr int P = 257;
;     f32x4 v[8];
; #pragma unroll
;     for (int i = 0; i < 8; ++i) { const int idx4 = i * 512 + tid, r = idx4 >> 6, c4 = (idx4 & 63) * 4;
;         v[i] = __builtin_nontemporal_load((const f32x4*)(src + (size_t)(k0 + r) * N + n0 + c4)); }
; #pragma unroll
;     for (int i = 0; i < 8; ++i) { const int idx4 = i * 512 + tid, r = idx4 >> 6, c4 = (idx4 & 63) * 4;
;         f32x4 w = v[i]; if (scale) w *= scale[k0 + r]; if (nscale) w *= *(const f32x4*)(nscale + n0 + c4);
;         tile[r * P + c4] = w[0]; tile[r * P + c4 + 1] = w[1]; tile[r * P + c4 + 2] = w[2]; tile[r * P + c4 + 3] = w[3]; }
;     __syncthreads();
.Lcva_dp_done:
	v_lshlrev_b32_e32 v16, s36, v2
	s_lshl_b32 s38, 8, s36
	v_add_u32_e32 v16, v16, v3
	global_load_dwordx4 v[20:23], v16, s[24:25] nt
	s_add_u32 s24, s24, s38
	s_addc_u32 s25, s25, 0
	global_load_dwordx4 v[24:27], v16, s[24:25] nt
	s_add_u32 s24, s24, s38
	s_addc_u32 s25, s25, 0
	global_load_dwordx4 v[28:31], v16, s[24:25] nt
	s_add_u32 s24, s24, s38
	s_addc_u32 s25, s25, 0
	global_load_dwordx4 v[32:35], v16, s[24:25] nt
	s_add_u32 s24, s24, s38
	s_addc_u32 s25, s25, 0
	global_load_dwordx4 v[36:39], v16, s[24:25] nt
	s_add_u32 s24, s24, s38
	s_addc_u32 s25, s25, 0
	global_load_dwordx4 v[40:43], v16, s[24:25] nt
	s_add_u32 s24, s24, s38
	s_addc_u32 s25, s25, 0
	global_load_dwordx4 v[44:47], v16, s[24:25] nt
	s_add_u32 s24, s24, s38
	s_addc_u32 s25, s25, 0
	global_load_dwordx4 v[48:51], v16, s[24:25] nt
	s_cmp_lg_u32 s34, 0
	s_cbranch_scc1 .Lcva_ip_n0
	global_load_dword v52, v6, s[32:33] offset:0
	global_load_dword v54, v6, s[32:33] offset:32
	global_load_dword v56, v6, s[32:33] offset:64
	global_load_dword v58, v6, s[32:33] offset:96
	global_load_dword v60, v6, s[32:33] offset:128
	global_load_dword v62, v6, s[32:33] offset:160
	global_load_dword v64, v6, s[32:33] offset:192
	global_load_dword v66, v6, s[32:33] offset:224
	s_branch .Lcva_ip_done
.Lcva_ip_n0:
	s_cmp_lg_u32 s34, 1
	s_cbranch_scc1 .Lcva_ip_done
	global_load_dwordx4 v[52:55], v3, s[32:33]
.Lcva_ip_done:
	s_waitcnt vmcnt(0)
	s_branch .Lcva_body
.Lcva_top:
	s_waitcnt vmcnt(8)
.Lcva_body:
	s_mov_b32 s28, s26
	s_mov_b32 s29, s27
	s_mov_b32 s31, s37
	s_cmp_lg_u32 s34, 0
	s_cbranch_scc1 .Lcva_m_n0
	v_pk_mul_f32 v[20:21], v[20:21], v[52:53] op_sel_hi:[1,0]
	v_pk_mul_f32 v[22:23], v[22:23], v[52:53] op_sel_hi:[1,0]
	v_pk_mul_f32 v[24:25], v[24:25], v[54:55] op_sel_hi:[1,0]
	v_pk_mul_f32 v[26:27], v[26:27], v[54:55] op_sel_hi:[1,0]
	v_pk_mul_f32 v[28:29], v[28:29], v[56:57] op_sel_hi:[1,0]
	v_pk_mul_f32 v[30:31], v[30:31], v[56:57] op_sel_hi:[1,0]
	v_pk_mul_f32 v[32:33], v[32:33], v[58:59] op_sel_hi:[1,0]
	v_pk_mul_f32 v[34:35], v[34:35], v[58:59] op_sel_hi:[1,0]
	v_pk_mul_f32 v[36:37], v[36:37], v[60:61] op_sel_hi:[1,0]
	v_pk_mul_f32 v[38:39], v[38:39], v[60:61] op_sel_hi:[1,0]
	v_pk_mul_f32 v[40:41], v[40:41], v[62:63] op_sel_hi:[1,0]
	v_pk_mul_f32 v[42:43], v[42:43], v[62:63] op_sel_hi:[1,0]
	v_pk_mul_f32 v[44:45], v[44:45], v[64:65] op_sel_hi:[1,0]
	v_pk_mul_f32 v[46:47], v[46:47], v[64:65] op_sel_hi:[1,0]
	v_pk_mul_f32 v[48:49], v[48:49], v[66:67] op_sel_hi:[1,0]
	v_pk_mul_f32 v[50:51], v[50:51], v[66:67] op_sel_hi:[1,0]
	s_branch .Lcva_m_done
.Lcva_m_n0:
	s_cmp_lg_u32 s34, 1
	s_cbranch_scc1 .Lcva_m_done
	v_pk_mul_f32 v[20:21], v[20:21], v[52:53]
	v_pk_mul_f32 v[22:23], v[22:23], v[54:55]
	v_pk_mul_f32 v[24:25], v[24:25], v[52:53]
	v_pk_mul_f32 v[26:27], v[26:27], v[54:55]
	v_pk_mul_f32 v[28:29], v[28:29], v[52:53]
	v_pk_mul_f32 v[30:31], v[30:31], v[54:55]
	v_pk_mul_f32 v[32:33], v[32:33], v[52:53]
	v_pk_mul_f32 v[34:35], v[34:35], v[54:55]
	v_pk_mul_f32 v[36:37], v[36:37], v[52:53]
	v_pk_mul_f32 v[38:39], v[38:39], v[54:55]
	v_pk_mul_f32 v[40:41], v[40:41], v[52:53]
	v_pk_mul_f32 v[42:43], v[42:43], v[54:55]
	v_pk_mul_f32 v[44:45], v[44:45], v[52:53]
	v_pk_mul_f32 v[46:47], v[46:47], v[54:55]
	v_pk_mul_f32 v[48:49], v[48:49], v[52:53]
	v_pk_mul_f32 v[50:51], v[50:51], v[54:55]
.Lcva_m_done:
	ds_write2_b32 v8, v20, v21 offset1:1
	ds_write2_b32 v8, v22, v23 offset0:2 offset1:3
	ds_write2_b32 v9, v24, v25 offset1:1
	ds_write2_b32 v9, v26, v27 offset0:2 offset1:3
	ds_write2_b32 v10, v28, v29 offset1:1
	ds_write2_b32 v10, v30, v31 offset0:2 offset1:3
	ds_write2_b32 v11, v32, v33 offset1:1
	ds_write2_b32 v11, v34, v35 offset0:2 offset1:3
	ds_write2_b32 v12, v36, v37 offset1:1
	ds_write2_b32 v12, v38, v39 offset0:2 offset1:3
	ds_write2_b32 v13, v40, v41 offset1:1
	ds_write2_b32 v13, v42, v43 offset0:2 offset1:3
	ds_write2_b32 v14, v44, v45 offset1:1
	ds_write2_b32 v14, v46, v47 offset0:2 offset1:3
	ds_write2_b32 v15, v48, v49 offset1:1
	ds_write2_b32 v15, v50, v51 offset0:2 offset1:3
	v_lshlrev_b32_e32 v17, s31, v4
	s_lshl_b32 s30, 32, s31
	v_add_u32_e32 v17, v17, v5
	s_add_i32 s23, s18, s19
	s_waitcnt lgkmcnt(0)
	s_barrier
	s_cmp_lt_i32 s23, 0
	s_cbranch_scc1 .Lcva_nonext
	s_cmp_ge_i32 s23, s20
	s_cbranch_scc1 .Lcva_nonext
	s_cmpk_lt_u32 s23, 0x800
	s_cbranch_scc0 .Lcva_dn_k12
	s_lshr_b32 s38, s23, 6
	s_and_b32 s39, s23, 63
	s_lshl_b32 s6, s21, 27
	s_lshl_b32 s7, s38, 22
	s_add_u32 s6, s6, s7
	s_lshl_b32 s7, s39, 10
	s_add_u32 s6, s6, s7
	s_add_u32 s24, s56, s6
	s_addc_u32 s25, s57, 0
	s_lshl_b32 s6, s21, 26
	s_lshl_b32 s7, s39, 20
	s_add_u32 s6, s6, s7
	s_lshl_b32 s7, s38, 7
	s_add_u32 s6, s6, s7
	s_add_u32 s26, s16, s6
	s_addc_u32 s27, s17, 0
	s_lshl_b32 s6, s21, 13
	s_lshl_b32 s7, s38, 8
	s_add_u32 s6, s6, s7
	s_add_u32 s32, s54, s6
	s_addc_u32 s33, s55, 0
	s_mov_b32 s36, 16
	s_mov_b32 s37, 12
	s_mov_b32 s34, 0
	s_branch .Lcva_dn_done

; __device__ __forceinline__ unsigned pk_bf16(float lo, float hi) { unsigned r; asm volatile("v_cvt_pk_bf16_f32 %0, %1, %2" : "=v"(r) : "v"(lo), "v"(hi)); return r; }
; __device__ __forceinline__ void tr_tile(LAS float* tile, const float* src, int N, bf16_t* dst, int Kd, int k0, int n0, const float* scale, const float* nscale, int tid) {
;     ...
;     for (int i = 0; i < 8; ++i) { const int idx = i * 512 + tid, n = idx >> 4, k4 = (idx & 15) * 4;
;         u32x2 w; w.x = pk_bf16(tile[(k4) * P + n], tile[(k4 + 1) * P + n]); w.y = pk_bf16(tile[(k4 + 2) * P + n], tile[(k4 + 3) * P + n]);
;         *(u32x2*)(dst + (size_t)(n0 + n) * Kd + k0 + k4) = w; }
;     __syncthreads();
.Lcva_in_done:
	s_mov_b32 s35, 1
	s_branch .Lcva_rd
.Lcva_nonext:
	s_mov_b32 s35, 0
.Lcva_rd:
	ds_read_b32 v68, v7
	ds_read_b32 v69, v7 offset:1028
	ds_read_b32 v70, v7 offset:2056
	ds_read_b32 v71, v7 offset:3084
	ds_read_b32 v72, v7 offset:128
	ds_read_b32 v73, v7 offset:1156
	ds_read_b32 v74, v7 offset:2184
	ds_read_b32 v75, v7 offset:3212
	ds_read_b32 v76, v7 offset:256
	ds_read_b32 v77, v7 offset:1284
	ds_read_b32 v78, v7 offset:2312
	ds_read_b32 v79, v7 offset:3340
	s_waitcnt lgkmcnt(8)
	ds_read_b32 v80, v7 offset:384
	ds_read_b32 v81, v7 offset:1412
	ds_read_b32 v82, v7 offset:2440
	ds_read_b32 v83, v7 offset:3468
	v_cvt_pk_bf16_f32 v68, v68, v69
	v_cvt_pk_bf16_f32 v69, v70, v71
	global_store_dwordx2 v17, v[68:69], s[28:29]
	s_add_u32 s28, s28, s30
	s_addc_u32 s29, s29, 0
	s_waitcnt lgkmcnt(8)
	ds_read_b32 v84, v7 offset:512
	ds_read_b32 v85, v7 offset:1540
	ds_read_b32 v86, v7 offset:2568
	ds_read_b32 v87, v7 offset:3596
	v_cvt_pk_bf16_f32 v72, v72, v73
	v_cvt_pk_bf16_f32 v73, v74, v75
	global_store_dwordx2 v17, v[72:73], s[28:29]
	s_add_u32 s28, s28, s30
	s_addc_u32 s29, s29, 0
	s_waitcnt lgkmcnt(8)
	ds_read_b32 v88, v7 offset:640
	ds_read_b32 v89, v7 offset:1668
	ds_read_b32 v90, v7 offset:2696
	ds_read_b32 v91, v7 offset:3724
	v_cvt_pk_bf16_f32 v76, v76, v77
	v_cvt_pk_bf16_f32 v77, v78, v79
	global_store_dwordx2 v17, v[76:77], s[28:29]
	s_add_u32 s28, s28, s30
	s_addc_u32 s29, s29, 0
	s_waitcnt lgkmcnt(8)
	ds_read_b32 v92, v7 offset:768
	ds_read_b32 v93, v7 offset:1796
	ds_read_b32 v94, v7 offset:2824
	ds_read_b32 v95, v7 offset:3852
	v_cvt_pk_bf16_f32 v80, v80, v81
	v_cvt_pk_bf16_f32 v81, v82, v83
	global_store_dwordx2 v17, v[80:81], s[28:29]
	s_add_u32 s28, s28, s30
	s_addc_u32 s29, s29, 0
	s_waitcnt lgkmcnt(8)
	ds_read_b32 v96, v7 offset:896
	ds_read_b32 v97, v7 offset:1924
	ds_read_b32 v98, v7 offset:2952
	ds_read_b32 v99, v7 offset:3980
	v_cvt_pk_bf16_f32 v84, v84, v85
	v_cvt_pk_bf16_f32 v85, v86, v87
	global_store_dwordx2 v17, v[84:85], s[28:29]
	s_add_u32 s28, s28, s30
	s_addc_u32 s29, s29, 0
	s_waitcnt lgkmcnt(8)
	v_cvt_pk_bf16_f32 v88, v88, v89
	v_cvt_pk_bf16_f32 v89, v90, v91
	global_store_dwordx2 v17, v[88:89], s[28:29]
	s_add_u32 s28, s28, s30
	s_addc_u32 s29, s29, 0
	s_waitcnt lgkmcnt(4)
	v_cvt_pk_bf16_f32 v92, v92, v93
	v_cvt_pk_bf16_f32 v93, v94, v95
	global_store_dwordx2 v17, v[92:93], s[28:29]
	s_add_u32 s28, s28, s30
	s_addc_u32 s29, s29, 0
	s_waitcnt lgkmcnt(0)
	v_cvt_pk_bf16_f32 v96, v96, v97
	v_cvt_pk_bf16_f32 v97, v98, v99
	global_store_dwordx2 v17, v[96:97], s[28:29]
	s_barrier
	s_mov_b32 s18, s23
	s_cmp_lg_u32 s35, 0
	s_cbranch_scc1 .Lcva_top
	s_cmp_eq_u32 s22, 1
	s_cbranch_scc1 .LBB0_281
	s_branch .LBB0_139

; __device__ __forceinline__ int launder(int v) { asm volatile("" : "+v"(v)); return v; }
; __device__ __forceinline__ void run_phase(const Params& p, int ph, LAS unsigned char* lds, const int tid, const int bid) {
;     ...
;         if (l == 0 && bid >= 80) for (int it = bid - 80; it < 1440; it += G - 80) conv_item(p, 1, it, lds, launder(tid)); }
.Lp5_noshadow:
	s_cmp_lt_u32 s81, 7
	s_cselect_b64 s[0:1], -1, 0
	s_cmpk_gt_i32 s82, 0x4f
	s_cselect_b64 s[6:7], -1, 0
	s_cmpk_lt_u32 s82, 0x5f0
	s_cselect_b64 s[8:9], -1, 0
	s_and_b64 s[0:1], s[0:1], s[8:9]
	s_and_b64 s[0:1], s[0:1], s[6:7]
	s_andn2_b64 vcc, exec, s[0:1]
	s_cbranch_vccnz .LBB0_281
	s_add_i32 s18, s82, 0xffffffb0
	s_add_i32 s19, s42, 0xffffffb0
	s_movk_i32 s20, 0x5a0
	s_mov_b32 s21, 1
	s_mov_b32 s22, 1
	s_branch .Lcva_run

; __device__ __forceinline__ unsigned pk_bf16(float lo, float hi) { unsigned r; asm volatile("v_cvt_pk_bf16_f32 %0, %1, %2" : "=v"(r) : "v"(lo), "v"(hi)); return r; }
; __device__ void phase0(const Params& p, LAS unsigned char* lds, const int tid_in, const int bid) {
;     ...
;     for (int it = bid; it < NT_L + NROWI; it += gridDim.x) {
;         if (it < NT_L) {
;             conv_item(p, 0, it, lds, tid);
;         } else {
;             const int row = (it - NT_L) * 8 + wid;
;             float* xf = (float*)(pws(p) + OFF_XF) + (size_t)row * D; bf16_t* xb = (bf16_t*)(pws(p) + OFF_XB) + (size_t)row * D; float* rsq = (float*)(pws(p) + OFF_RSQ);
;             const float* src = nullptr;
;             if (row < MS) src = p.x_sample + (size_t)row * D;
;             else if (row < MR) { const int pr = row - MS, b = pr / LP, pp = pr % LP; src = pp < 16 ? p.meta + (size_t)pp * D : p.x_prompt + ((size_t)b * 2048 + pp - 16) * D; }
;             f32x4 v[8];
; #pragma unroll
;             for (int i = 0; i < 8; ++i) { v[i] = (f32x4){0.f, 0.f, 0.f, 0.f}; if (src) v[i] = *(const f32x4*)(src + i * 256 + lane * 4); }
;             float ss = 0.f;
; #pragma unroll
;             for (int i = 0; i < 8; ++i) { const int c = i * 256 + lane * 4;
;                 *(f32x4*)(xf + c) = v[i]; u32x2 w; w.x = pk_bf16(v[i][0], v[i][1]); w.y = pk_bf16(v[i][2], v[i][3]); *(u32x2*)(xb + c) = w;
;                 ss += v[i][0] * v[i][0] + v[i][1] * v[i][1] + v[i][2] * v[i][2] + v[i][3] * v[i][3]; }
;             ss = wave_sum(ss);
;             if (lane == 0) { rsq[row] = ss; rsq[MPAD + row] = 0.f; }
;         }
.LBB0_585:
	s_or_b64 exec, exec, s[0:1]
	s_cmpk_lg_u32 s42, 0x100
	s_cbranch_scc1 .Lcvb_tryfwd
	s_bitcmp1_b32 s82, 3
	s_cbranch_scc1 .Lcvb_skip
.Lcvb_tryfwd:
	s_cmpk_gt_i32 s82, 0xb3f
	s_cbranch_scc1 .Lcvb_skip
	s_branch .Lcvb_fwd
.Lcvb_ret0:
	s_mov_b32 s82, s18
.Lcvb_skip:
	s_cmpk_gt_i32 s82, 0xfdf
	s_cbranch_scc1 .LBB0_660
	s_waitcnt vmcnt(0)
	v_lshlrev_b32_e32 v2, 2, v244
	v_add_u32_e32 v4, 0x200, v244
	v_add_u32_e32 v5, 0x400, v244
	v_add_u32_e32 v6, 0x600, v244
	v_add_u32_e32 v7, 0x800, v244
	v_add_u32_e32 v8, 0xa00, v244
	v_add_u32_e32 v9, 0xc00, v244
	v_add_u32_e32 v10, 0xe00, v244
	v_ashrrev_i32_e32 v39, 6, v244
	v_and_b32_e32 v40, 0xfc, v2
	v_ashrrev_i32_e32 v43, 6, v4
	v_ashrrev_i32_e32 v74, 6, v5
	v_ashrrev_i32_e32 v75, 6, v6
	v_ashrrev_i32_e32 v76, 6, v7
	v_ashrrev_i32_e32 v77, 6, v8
	v_ashrrev_i32_e32 v78, 6, v9
	v_ashrrev_i32_e32 v79, 6, v10
	s_movk_i32 s0, 0x404
	v_and_b32_e32 v42, 60, v2
	v_and_b32_e32 v3, 63, v244
	v_lshlrev_b32_e32 v0, 2, v40
	v_mul_lo_u32 v81, v39, s0
	v_mul_lo_u32 v82, v43, s0
	v_mul_lo_u32 v83, v74, s0
	v_mul_lo_u32 v84, v75, s0
	v_mul_lo_u32 v85, v76, s0
	v_mul_lo_u32 v86, v77, s0
	v_mul_lo_u32 v87, v78, s0
	v_mul_lo_u32 v88, v79, s0
	v_mad_u32_u24 v2, v42, s0, 0
	v_readlane_b32 s0, v254, 20
	v_lshlrev_b32_e32 v38, 2, v3
	v_add_u32_e32 v80, 0, v0
	v_ashrrev_i32_e32 v89, 4, v244
	v_ashrrev_i32_e32 v91, 4, v4
	v_ashrrev_i32_e32 v93, 4, v5
	v_ashrrev_i32_e32 v95, 4, v6
	v_ashrrev_i32_e32 v97, 4, v7
	v_ashrrev_i32_e32 v99, 4, v8
	v_ashrrev_i32_e32 v101, 4, v9
	v_ashrrev_i32_e32 v103, 4, v10
	v_lshl_add_u64 v[44:45], s[56:57], 0, v[0:1]
	v_lshlrev_b32_e32 v0, 1, v42
	v_readlane_b32 s1, v254, 21
	v_lshl_add_u32 v90, v89, 2, v2
	v_lshl_add_u32 v92, v91, 2, v2
	v_lshl_add_u32 v94, v93, 2, v2
	v_lshl_add_u32 v96, v95, 2, v2
	v_lshl_add_u32 v98, v97, 2, v2
	v_lshl_add_u32 v100, v99, 2, v2
	v_lshl_add_u32 v102, v101, 2, v2
	v_lshl_add_u32 v104, v103, 2, v2
	v_or_b32_e32 v2, 0x400, v38
	v_or_b32_e32 v4, 0x500, v38
	v_or_b32_e32 v6, 0x600, v38
	v_or_b32_e32 v8, 0x700, v38
	v_lshl_add_u64 v[46:47], s[0:1], 0, v[0:1]
	v_lshlrev_b32_e32 v0, 3, v3
	v_add_u32_e32 v41, 0xffffa600, v39
	v_cmp_eq_u32_e64 s[6:7], 0, v3
	v_lshl_add_u64 v[48:49], s[68:69], 0, v[0:1]
	s_cmpk_lg_u32 s42, 0x100
	s_cbranch_scc1 .Lp0_fwd0
	s_bitcmp1_b32 s82, 3
	s_cbranch_scc0 .Lp0_fwd0
	s_sub_i32 s0, 0xfdf, s82
	s_andn2_b32 s0, s0, 0xff
	s_add_i32 s82, s82, s0
.Lp0_fwd0:
	s_lshl_b32 s12, s82, 3
	s_lshl_b32 s13, s82, 8
	s_lshl_b32 s14, s82, 5
	v_lshlrev_b32_e32 v50, 2, v2
	v_lshlrev_b32_e32 v52, 2, v4
	v_lshlrev_b32_e32 v54, 2, v6
	v_lshlrev_b32_e32 v56, 2, v8
	s_branch .LBB0_591
.LBB0_589:
	s_waitcnt lgkmcnt(0)

; __device__ void phase0(const Params& p, LAS unsigned char* lds, const int tid_in, const int bid) {
;     ...
;     for (int it = bid; it < NT_L + NROWI; it += gridDim.x) {
;         if (it < NT_L) {
;             conv_item(p, 0, it, lds, tid);
.LBB0_620:
	s_or_b64 exec, exec, s[0:1]
	s_mov_b64 s[0:1], 0
.LBB0_621:
	s_branch .LBB0_590
.Lcvb_bwd:
	s_mov_b32 s18, s82
	s_sub_i32 s19, 0, s42
	s_movk_i32 s20, 0xb40
	s_mov_b32 s21, 0
	s_mov_b32 s22, 3
	s_branch .Lcvb_run
.Lcvb_fwd:
	s_mov_b32 s18, s82
	s_mov_b32 s19, s42
	s_movk_i32 s20, 0xb40
	s_mov_b32 s21, 0
	s_mov_b32 s22, 0
	s_branch .Lcvb_run

; __device__ __forceinline__ unsigned pk_bf16(float lo, float hi) { unsigned r; asm volatile("v_cvt_pk_bf16_f32 %0, %1, %2" : "=v"(r) : "v"(lo), "v"(hi)); return r; }
; __device__ __forceinline__ void tr_tile(LAS float* tile, const float* src, int N, bf16_t* dst, int Kd, int k0, int n0, const float* scale, const float* nscale, int tid) {
;     ...
;     for (int i = 0; i < 8; ++i) { const int idx = i * 512 + tid, n = idx >> 4, k4 = (idx & 15) * 4;
;         u32x2 w; w.x = pk_bf16(tile[(k4) * P + n], tile[(k4 + 1) * P + n]); w.y = pk_bf16(tile[(k4 + 2) * P + n], tile[(k4 + 3) * P + n]);
;         *(u32x2*)(dst + (size_t)(n0 + n) * Kd + k0 + k4) = w; }
;     __syncthreads();
.Lcvb_rd:
	ds_read_b32 v68, v7
	ds_read_b32 v69, v7 offset:1028
	ds_read_b32 v70, v7 offset:2056
	ds_read_b32 v71, v7 offset:3084
	ds_read_b32 v72, v7 offset:128
	ds_read_b32 v73, v7 offset:1156
	ds_read_b32 v74, v7 offset:2184
	ds_read_b32 v75, v7 offset:3212
	ds_read_b32 v76, v7 offset:256
	ds_read_b32 v77, v7 offset:1284
	ds_read_b32 v78, v7 offset:2312
	ds_read_b32 v79, v7 offset:3340
	s_waitcnt lgkmcnt(8)
	ds_read_b32 v80, v7 offset:384
	ds_read_b32 v81, v7 offset:1412
	ds_read_b32 v82, v7 offset:2440
	ds_read_b32 v83, v7 offset:3468
	v_cvt_pk_bf16_f32 v68, v68, v69
	v_cvt_pk_bf16_f32 v69, v70, v71
	global_store_dwordx2 v17, v[68:69], s[28:29]
	s_add_u32 s28, s28, s30
	s_addc_u32 s29, s29, 0
	s_waitcnt lgkmcnt(8)
	ds_read_b32 v84, v7 offset:512
	ds_read_b32 v85, v7 offset:1540
	ds_read_b32 v86, v7 offset:2568
	ds_read_b32 v87, v7 offset:3596
	v_cvt_pk_bf16_f32 v72, v72, v73
	v_cvt_pk_bf16_f32 v73, v74, v75
	global_store_dwordx2 v17, v[72:73], s[28:29]
	s_add_u32 s28, s28, s30
	s_addc_u32 s29, s29, 0
	s_waitcnt lgkmcnt(8)
	ds_read_b32 v88, v7 offset:640
	ds_read_b32 v89, v7 offset:1668
	ds_read_b32 v90, v7 offset:2696
	ds_read_b32 v91, v7 offset:3724
	v_cvt_pk_bf16_f32 v76, v76, v77
	v_cvt_pk_bf16_f32 v77, v78, v79
	global_store_dwordx2 v17, v[76:77], s[28:29]
	s_add_u32 s28, s28, s30
	s_addc_u32 s29, s29, 0
	s_waitcnt lgkmcnt(8)
	ds_read_b32 v92, v7 offset:768
	ds_read_b32 v93, v7 offset:1796
	ds_read_b32 v94, v7 offset:2824
	ds_read_b32 v95, v7 offset:3852
	v_cvt_pk_bf16_f32 v80, v80, v81
	v_cvt_pk_bf16_f32 v81, v82, v83
	global_store_dwordx2 v17, v[80:81], s[28:29]
	s_add_u32 s28, s28, s30
	s_addc_u32 s29, s29, 0
	s_waitcnt lgkmcnt(8)
	ds_read_b32 v96, v7 offset:896
	ds_read_b32 v97, v7 offset:1924
	ds_read_b32 v98, v7 offset:2952
	ds_read_b32 v99, v7 offset:3980
	v_cvt_pk_bf16_f32 v84, v84, v85
	v_cvt_pk_bf16_f32 v85, v86, v87
	global_store_dwordx2 v17, v[84:85], s[28:29]
	s_add_u32 s28, s28, s30
	s_addc_u32 s29, s29, 0
	s_waitcnt lgkmcnt(8)
	v_cvt_pk_bf16_f32 v88, v88, v89
	v_cvt_pk_bf16_f32 v89, v90, v91
	global_store_dwordx2 v17, v[88:89], s[28:29]
	s_add_u32 s28, s28, s30
	s_addc_u32 s29, s29, 0
	s_waitcnt lgkmcnt(4)
	v_cvt_pk_bf16_f32 v92, v92, v93
	v_cvt_pk_bf16_f32 v93, v94, v95
	global_store_dwordx2 v17, v[92:93], s[28:29]
	s_add_u32 s28, s28, s30
	s_addc_u32 s29, s29, 0
	s_waitcnt lgkmcnt(0)
	v_cvt_pk_bf16_f32 v96, v96, v97
	v_cvt_pk_bf16_f32 v97, v98, v99
	global_store_dwordx2 v17, v[96:97], s[28:29]
	s_barrier
	s_mov_b32 s18, s23
	s_cmp_lg_u32 s35, 0
	s_cbranch_scc1 .Lcvb_top
	s_cmp_eq_u32 s22, 0
	s_cbranch_scc1 .Lcvb_ret0
	s_branch .LBB0_660
